# attention: one s_barrier per task (XCD-local mode) re-aligns the 8 waves of a workgroup that now share one head's K/V tiles
# speedup vs baseline: 1.0210x; 1.0016x over previous
; __device__ __forceinline__ void attn_all(KArgs& a, LAS unsigned char* lds, int l) {
;     ...
;     for (int ti = gw; ti < tend; ti += ngw) {
;         const int b = xl ? (bid & 7) : ti / ntb, task = xl ? ti : ti - b * ntb;
.LBB0_493:
	s_and_b64 vcc, exec, s[16:17]
	s_cbranch_vccz .Lattn_nobar
	s_barrier
